# speedup vs baseline: 1.0011x; 1.0011x over previous
; __device__ __forceinline__ unsigned pk2(float lo, float hi) { unsigned r; asm("v_cvt_pk_bf16_f32 %0, %1, %2" : "=v"(r) : "v"(lo), "v"(hi)); return r; }
; __device__ __forceinline__ void st16_wt(void* p, u32x4 v) { asm volatile("global_store_dwordx4 %0, %1, off sc1\n\ts_nop 1" :: "v"(p), "v"(v) : "memory"); }
; #define PG8_WAIT_V(n) asm volatile("s_waitcnt vmcnt(" #n ")" ::: "memory")
; #define PG8_WAIT_L(n) asm volatile("s_waitcnt lgkmcnt(" #n ")" ::: "memory")
; #define PG8_BAR __builtin_amdgcn_s_barrier()
; #define PG8_SCHED __builtin_amdgcn_sched_barrier(0)
; template <class Epi, class Pre, bool AG = false>
; __device__ __forceinline__ void gemm_phase(LAS unsigned char* lds, const Gemm g, const StaticOrder& S, const Epi& E, const Pre& P) {
;     ...
;             PG8_WAIT_V(8); PG8_WAIT_L(0); PG8_BAR; PG8_MMA(1, 0, At, B0); PG8_MMA(1, 1, At, B1); PG8_BAR; PG8_SCHED;
;     __device__ __forceinline__ void operator()(const AccT& acc, const pg8::Unit& u, int ui, int wr, int wc, int fr, int fq) const {
;         const int row0 = u.pm * 256 + wr * 64 + fr, col0 = u.pn * 128 + wc * 32 + 8 * fq;
;         float rs[2][4]; lane_rstd(lds, ui, wr, fr, rs);
; #pragma unroll
;         for (int ai = 0; ai < 2; ++ai)
; #pragma unroll
;             for (int m = 0; m < 4; ++m) {
;                 const float s = rs[ai][m]; u16* op = act + (size_t)(row0 + ai * 128 + m * 16) * FF + col0;
;                 const float c1 = -1.4426950408889634f * s, c2 = s * s;
;                 u32x4 w;
; #pragma unroll
;                 for (int n = 0; n < 2; ++n)
; #pragma unroll
;                     for (int hh = 0; hh < 2; ++hh) {
;                         const f32x2 ga = {acc[ai][0][m][n][2 * hh], acc[ai][0][m][n][2 * hh + 1]}, ua = {acc[ai][1][m][n][2 * hh], acc[ai][1][m][n][2 * hh + 1]};
;                         f32x2 t = ga * c1; t.x = fminf(t.x, 60.0f); t.y = fminf(t.y, 60.0f);
;                         f32x2 e; e.x = __builtin_amdgcn_exp2f(t.x); e.y = __builtin_amdgcn_exp2f(t.y);
;                         const f32x2 d = e + 1.0f;
;                         const float rp = __builtin_amdgcn_rcpf(d.x * d.y);
;                         const f32x2 r = {d.y * rp, d.x * rp};
;                         const f32x2 o = ((ga * ua) * c2) * r;
;                         w[2 * n + hh] = pk2(o.x, o.y);
;                     }
;                 st16_wt(op, w);
;             }
.Lgu_last_sp2:
	v_mfma_f32_16x16x32_bf16 v[58:61], v[140:143], v[174:177], v[58:61]
	v_and_b32_e32 v178, 15, v234
	s_lshl_b32 s99, s71, 8
	s_add_i32 s99, s99, s56
	v_or_b32_e32 v179, s99, v178
	s_lshl_b32 s99, s70, 10
	s_add_i32 s99, s60, s99
	v_mfma_f32_16x16x32_bf16 v[50:53], v[150:153], v[174:177], v[50:53]
	v_lshl_add_u32 v184, v178, 2, s99
	ds_read2_b32 v[186:187], v184 offset1:16
	ds_read2_b32 v[188:189], v184 offset0:32 offset1:48
	s_lshl_b32 s99, s62, 7
	v_lshrrev_b32_e32 v180, 1, v234
	v_and_or_b32 v180, v180, 24, s99
	v_mfma_f32_16x16x32_bf16 v[42:45], v[140:143], v[198:201], v[42:45]
	v_or_b32_e32 v180, s57, v180
	v_ashrrev_i32_e32 v181, 31, v180
	v_mov_b64_e32 v[190:191], s[8:9]
	v_mad_i64_i32 v[182:183], vcc, v179, s37, v[190:191]
	v_lshlrev_b64 v[180:181], 1, v[180:181]
	s_mov_b32 s100, 0x16000
	v_mfma_f32_16x16x32_bf16 v[34:37], v[150:153], v[198:201], v[34:37]
	s_mov_b32 s101, 0
	v_lshl_add_u64 v[182:183], v[182:183], 0, v[180:181]
	s_waitcnt lgkmcnt(0)
	v_mul_f32_e32 v190, 0xbfb8aa3b, v186
	v_mul_f32_e32 v193, v186, v186
	v_rcp_f32_e32 v192, v193
	v_mfma_f32_16x16x32_bf16 v[26:29], v[140:143], v[206:209], v[26:29]
	v_pk_mul_f32 v[222:223], v[122:123], v[190:191] op_sel_hi:[1,0]
	v_pk_mul_f32 v[224:225], v[124:125], v[190:191] op_sel_hi:[1,0]
	v_pk_mul_f32 v[226:227], v[114:115], v[190:191] op_sel_hi:[1,0]
	v_pk_mul_f32 v[228:229], v[116:117], v[190:191] op_sel_hi:[1,0]
	v_exp_f32_e32 v222, v222
	v_exp_f32_e32 v223, v223
	v_mfma_f32_16x16x32_bf16 v[18:21], v[150:153], v[206:209], v[18:21]
	v_exp_f32_e32 v224, v224
	v_exp_f32_e32 v225, v225
	v_exp_f32_e32 v226, v226
	v_exp_f32_e32 v227, v227
	v_exp_f32_e32 v228, v228
	v_exp_f32_e32 v229, v229
	v_mfma_f32_16x16x32_bf16 v[10:13], v[140:143], v[214:217], v[10:13]
	v_pk_fma_f32 v[222:223], v[222:223], v[192:193], v[192:193] op_sel_hi:[1,0,0]
	v_pk_fma_f32 v[224:225], v[224:225], v[192:193], v[192:193] op_sel_hi:[1,0,0]
	v_pk_fma_f32 v[226:227], v[226:227], v[192:193], v[192:193] op_sel_hi:[1,0,0]
	v_pk_fma_f32 v[228:229], v[228:229], v[192:193], v[192:193] op_sel_hi:[1,0,0]
	v_pk_mul_f32 v[122:123], v[122:123], v[126:127]
	v_pk_mul_f32 v[124:125], v[124:125], v[128:129]
	v_mfma_f32_16x16x32_bf16 v[6:9], v[150:153], v[214:217], v[6:9]
	v_pk_mul_f32 v[114:115], v[114:115], v[118:119]
	v_pk_mul_f32 v[116:117], v[116:117], v[120:121]
	v_rcp_f32_e32 v222, v222
	v_rcp_f32_e32 v223, v223
	v_rcp_f32_e32 v224, v224
	v_rcp_f32_e32 v225, v225
	v_mfma_f32_16x16x32_bf16 v[58:61], v[144:147], v[194:197], v[58:61]
	v_rcp_f32_e32 v226, v226
	v_rcp_f32_e32 v227, v227
	v_rcp_f32_e32 v228, v228
	v_rcp_f32_e32 v229, v229
	s_nop 0
	v_pk_mul_f32 v[122:123], v[122:123], v[222:223]
	v_mfma_f32_16x16x32_bf16 v[50:53], v[154:157], v[194:197], v[50:53]
	v_pk_mul_f32 v[124:125], v[124:125], v[224:225]
	v_pk_mul_f32 v[114:115], v[114:115], v[226:227]
	v_pk_mul_f32 v[116:117], v[116:117], v[228:229]
	v_cvt_pk_bf16_f32 v246, v122, v123
	v_cvt_pk_bf16_f32 v247, v124, v125
	v_cvt_pk_bf16_f32 v248, v114, v115
	v_mfma_f32_16x16x32_bf16 v[42:45], v[144:147], v[202:205], v[42:45]
	v_cvt_pk_bf16_f32 v249, v116, v117
	global_store_dwordx4 v[182:183], v[246:249], off sc1
	s_nop 1
	v_lshl_add_u64 v[182:183], v[182:183], 0, s[100:101]
	v_mul_f32_e32 v190, 0xbfb8aa3b, v187
	v_mul_f32_e32 v193, v187, v187
	v_mfma_f32_16x16x32_bf16 v[34:37], v[154:157], v[202:205], v[34:37]
	v_rcp_f32_e32 v192, v193
	v_pk_mul_f32 v[222:223], v[106:107], v[190:191] op_sel_hi:[1,0]
	v_pk_mul_f32 v[224:225], v[108:109], v[190:191] op_sel_hi:[1,0]
	v_pk_mul_f32 v[226:227], v[98:99], v[190:191] op_sel_hi:[1,0]
	v_pk_mul_f32 v[228:229], v[100:101], v[190:191] op_sel_hi:[1,0]
	v_exp_f32_e32 v222, v222
	v_mfma_f32_16x16x32_bf16 v[26:29], v[144:147], v[210:213], v[26:29]
	v_exp_f32_e32 v223, v223
	v_exp_f32_e32 v224, v224
	v_exp_f32_e32 v225, v225
	v_exp_f32_e32 v226, v226
	v_exp_f32_e32 v227, v227
	v_exp_f32_e32 v228, v228
	v_mfma_f32_16x16x32_bf16 v[18:21], v[154:157], v[210:213], v[18:21]
	v_exp_f32_e32 v229, v229
	v_pk_fma_f32 v[222:223], v[222:223], v[192:193], v[192:193] op_sel_hi:[1,0,0]
	v_pk_fma_f32 v[224:225], v[224:225], v[192:193], v[192:193] op_sel_hi:[1,0,0]
	v_pk_fma_f32 v[226:227], v[226:227], v[192:193], v[192:193] op_sel_hi:[1,0,0]
	v_pk_fma_f32 v[228:229], v[228:229], v[192:193], v[192:193] op_sel_hi:[1,0,0]
	v_pk_mul_f32 v[106:107], v[106:107], v[110:111]
	v_mfma_f32_16x16x32_bf16 v[10:13], v[144:147], v[218:221], v[10:13]
	v_pk_mul_f32 v[108:109], v[108:109], v[112:113]
	v_pk_mul_f32 v[98:99], v[98:99], v[102:103]
	v_pk_mul_f32 v[100:101], v[100:101], v[104:105]
	v_rcp_f32_e32 v222, v222
	v_rcp_f32_e32 v223, v223
	v_rcp_f32_e32 v224, v224
	v_mfma_f32_16x16x32_bf16 v[6:9], v[154:157], v[218:221], v[6:9]
	v_rcp_f32_e32 v225, v225
	v_rcp_f32_e32 v226, v226
	v_rcp_f32_e32 v227, v227
	v_rcp_f32_e32 v228, v228
	v_rcp_f32_e32 v229, v229
	s_nop 0
	v_mfma_f32_16x16x32_bf16 v[62:65], v[158:161], v[174:177], v[62:65]
	v_pk_mul_f32 v[106:107], v[106:107], v[222:223]
	v_pk_mul_f32 v[108:109], v[108:109], v[224:225]
	v_pk_mul_f32 v[98:99], v[98:99], v[226:227]
	v_pk_mul_f32 v[100:101], v[100:101], v[228:229]
	v_cvt_pk_bf16_f32 v250, v106, v107
	v_cvt_pk_bf16_f32 v251, v108, v109
	v_mfma_f32_16x16x32_bf16 v[54:57], v[166:169], v[174:177], v[54:57]
	v_cvt_pk_bf16_f32 v252, v98, v99
	v_cvt_pk_bf16_f32 v253, v100, v101
	global_store_dwordx4 v[182:183], v[250:253], off sc1
	s_nop 1
	v_lshl_add_u64 v[182:183], v[182:183], 0, s[100:101]
	v_mul_f32_e32 v190, 0xbfb8aa3b, v188
	v_mfma_f32_16x16x32_bf16 v[46:49], v[158:161], v[198:201], v[46:49]
	v_mul_f32_e32 v193, v188, v188
	v_rcp_f32_e32 v192, v193
	v_pk_mul_f32 v[222:223], v[90:91], v[190:191] op_sel_hi:[1,0]
; template <class Epi, class Pre, bool AG = false>
; __device__ __forceinline__ void gemm_phase(LAS unsigned char* lds, const Gemm g, const StaticOrder& S, const Epi& E, const Pre& P) {
;     ...
;             PG8_LDB(B0, 0, 0); PG8_LDB(B1, 0, 1); PG8_SCHED; PG8_LDA(At, 0, 0); PG8_STAGE(PG8_SA(1, 1), a1 + hstepA, voffA);
;             PG8_WAIT_V(8); PG8_WAIT_L(0); PG8_BAR; PG8_MMA(0, 0, At, B0); PG8_MMA(0, 1, At, B1); PG8_BAR; PG8_SCHED;
;             PG8_LDA(At, 0, 1); PG8_STAGE(PG8_SB(0, 0), b2, voffB); PG8_STAGE(PG8_SB(0, 1), b2 + hstep, voffB); PG8_STAGE(PG8_SA(0, 0), a2, voffA);
;             PG8_WAIT_V(8); PG8_WAIT_L(0); PG8_BAR; PG8_MMA(1, 0, At, B0); PG8_MMA(1, 1, At, B1); PG8_BAR; PG8_SCHED;
;             PG8_LDB(B0, 1, 0); PG8_LDB(B1, 1, 1); PG8_SCHED; PG8_LDA(At, 1, 0); PG8_STAGE(PG8_SA(0, 1), a2 + hstepA, voffA);
;             PG8_WAIT_V(8); PG8_WAIT_L(0); PG8_BAR; PG8_MMA(0, 0, At, B0); PG8_MMA(0, 1, At, B1); PG8_BAR; PG8_SCHED;
;             PG8_LDA(At, 1, 1); PG8_STAGE(PG8_SB(1, 0), b3, voffB); PG8_STAGE(PG8_SB(1, 1), b3 + hstep, voffB); PG8_STAGE(PG8_SA(1, 0), a3, voffA);
;             PG8_WAIT_V(8); PG8_WAIT_L(0); PG8_BAR; PG8_MMA(1, 0, At, B0); PG8_MMA(1, 1, At, B1); PG8_BAR; PG8_SCHED;
;     __device__ __forceinline__ void operator()(const AccT& acc, const pg8::Unit& u, int ui, int wr, int wc, int fr, int fq) const {
;     ...
;                 const float s = rs[ai][m]; u16* op = act + (size_t)(row0 + ai * 128 + m * 16) * FF + col0;
;                 const float c1 = -1.4426950408889634f * s, c2 = s * s;
;                 u32x4 w;
; #pragma unroll
;                 for (int n = 0; n < 2; ++n)
; #pragma unroll
;                     for (int hh = 0; hh < 2; ++hh) {
;                         const f32x2 ga = {acc[ai][0][m][n][2 * hh], acc[ai][0][m][n][2 * hh + 1]}, ua = {acc[ai][1][m][n][2 * hh], acc[ai][1][m][n][2 * hh + 1]};
;                         f32x2 t = ga * c1; t.x = fminf(t.x, 60.0f); t.y = fminf(t.y, 60.0f);
;                         f32x2 e; e.x = __builtin_amdgcn_exp2f(t.x); e.y = __builtin_amdgcn_exp2f(t.y);
;                         const f32x2 d = e + 1.0f;
;                         const float rp = __builtin_amdgcn_rcpf(d.x * d.y);
;                         const f32x2 r = {d.y * rp, d.x * rp};
;                         const f32x2 o = ((ga * ua) * c2) * r;
;                         w[2 * n + hh] = pk2(o.x, o.y);
;                     }
	v_pk_mul_f32 v[224:225], v[92:93], v[190:191] op_sel_hi:[1,0]
	v_pk_mul_f32 v[226:227], v[82:83], v[190:191] op_sel_hi:[1,0]
	v_pk_mul_f32 v[228:229], v[84:85], v[190:191] op_sel_hi:[1,0]
	v_mfma_f32_16x16x32_bf16 v[38:41], v[166:169], v[198:201], v[38:41]
	v_exp_f32_e32 v222, v222
	v_exp_f32_e32 v223, v223
	v_exp_f32_e32 v224, v224
	v_exp_f32_e32 v225, v225
	v_exp_f32_e32 v226, v226
	v_exp_f32_e32 v227, v227
	v_mfma_f32_16x16x32_bf16 v[30:33], v[158:161], v[206:209], v[30:33]
	v_exp_f32_e32 v228, v228
	v_exp_f32_e32 v229, v229
	v_pk_fma_f32 v[222:223], v[222:223], v[192:193], v[192:193] op_sel_hi:[1,0,0]
	v_pk_fma_f32 v[224:225], v[224:225], v[192:193], v[192:193] op_sel_hi:[1,0,0]
	v_pk_fma_f32 v[226:227], v[226:227], v[192:193], v[192:193] op_sel_hi:[1,0,0]
	v_pk_fma_f32 v[228:229], v[228:229], v[192:193], v[192:193] op_sel_hi:[1,0,0]
	v_mfma_f32_16x16x32_bf16 v[22:25], v[166:169], v[206:209], v[22:25]
	v_pk_mul_f32 v[90:91], v[90:91], v[94:95]
	v_pk_mul_f32 v[92:93], v[92:93], v[96:97]
	v_pk_mul_f32 v[82:83], v[82:83], v[86:87]
	v_pk_mul_f32 v[84:85], v[84:85], v[88:89]
	v_rcp_f32_e32 v222, v222
	v_rcp_f32_e32 v223, v223
	v_mfma_f32_16x16x32_bf16 v[14:17], v[158:161], v[214:217], v[14:17]
	v_rcp_f32_e32 v224, v224
	v_rcp_f32_e32 v225, v225
	v_rcp_f32_e32 v226, v226
	v_rcp_f32_e32 v227, v227
	v_rcp_f32_e32 v228, v228
	v_rcp_f32_e32 v229, v229
	v_mfma_f32_16x16x32_bf16 v[2:5], v[166:169], v[214:217], v[2:5]
	s_nop 0
	v_pk_mul_f32 v[90:91], v[90:91], v[222:223]
	v_pk_mul_f32 v[92:93], v[92:93], v[224:225]
	v_pk_mul_f32 v[82:83], v[82:83], v[226:227]
	v_pk_mul_f32 v[84:85], v[84:85], v[228:229]
	v_cvt_pk_bf16_f32 v246, v90, v91
	v_mfma_f32_16x16x32_bf16 v[62:65], v[162:165], v[194:197], v[62:65]
	v_cvt_pk_bf16_f32 v247, v92, v93
	v_cvt_pk_bf16_f32 v248, v82, v83
	v_cvt_pk_bf16_f32 v249, v84, v85
	global_store_dwordx4 v[182:183], v[246:249], off sc1
	s_nop 1
	v_lshl_add_u64 v[182:183], v[182:183], 0, s[100:101]
	v_mfma_f32_16x16x32_bf16 v[54:57], v[170:173], v[194:197], v[54:57]
	v_mul_f32_e32 v190, 0xbfb8aa3b, v189
	v_mul_f32_e32 v193, v189, v189
	v_rcp_f32_e32 v192, v193
	v_pk_mul_f32 v[222:223], v[74:75], v[190:191] op_sel_hi:[1,0]
	v_pk_mul_f32 v[224:225], v[76:77], v[190:191] op_sel_hi:[1,0]
	v_pk_mul_f32 v[226:227], v[66:67], v[190:191] op_sel_hi:[1,0]
	v_mfma_f32_16x16x32_bf16 v[46:49], v[162:165], v[202:205], v[46:49]
	v_pk_mul_f32 v[228:229], v[68:69], v[190:191] op_sel_hi:[1,0]
	v_exp_f32_e32 v222, v222
	v_exp_f32_e32 v223, v223
	v_exp_f32_e32 v224, v224
	v_exp_f32_e32 v225, v225
	v_exp_f32_e32 v226, v226
	v_mfma_f32_16x16x32_bf16 v[38:41], v[170:173], v[202:205], v[38:41]
	v_exp_f32_e32 v227, v227
	v_exp_f32_e32 v228, v228
	v_exp_f32_e32 v229, v229
	v_pk_fma_f32 v[222:223], v[222:223], v[192:193], v[192:193] op_sel_hi:[1,0,0]
	v_pk_fma_f32 v[224:225], v[224:225], v[192:193], v[192:193] op_sel_hi:[1,0,0]
	v_pk_fma_f32 v[226:227], v[226:227], v[192:193], v[192:193] op_sel_hi:[1,0,0]
	v_mfma_f32_16x16x32_bf16 v[30:33], v[162:165], v[210:213], v[30:33]
	v_pk_fma_f32 v[228:229], v[228:229], v[192:193], v[192:193] op_sel_hi:[1,0,0]
	v_pk_mul_f32 v[74:75], v[74:75], v[78:79]
	v_pk_mul_f32 v[76:77], v[76:77], v[80:81]
	v_pk_mul_f32 v[66:67], v[66:67], v[70:71]
	v_pk_mul_f32 v[68:69], v[68:69], v[72:73]
	v_rcp_f32_e32 v222, v222
	v_mfma_f32_16x16x32_bf16 v[22:25], v[170:173], v[210:213], v[22:25]
	v_rcp_f32_e32 v223, v223
	v_rcp_f32_e32 v224, v224
	v_rcp_f32_e32 v225, v225
	v_rcp_f32_e32 v226, v226
	v_rcp_f32_e32 v227, v227
	v_rcp_f32_e32 v228, v228
	v_mfma_f32_16x16x32_bf16 v[14:17], v[162:165], v[218:221], v[14:17]
	v_rcp_f32_e32 v229, v229
	s_nop 0
	v_pk_mul_f32 v[74:75], v[74:75], v[222:223]
	v_pk_mul_f32 v[76:77], v[76:77], v[224:225]
	v_pk_mul_f32 v[66:67], v[66:67], v[226:227]
	v_pk_mul_f32 v[68:69], v[68:69], v[228:229]
	v_mfma_f32_16x16x32_bf16 v[2:5], v[170:173], v[218:221], v[2:5]
	v_cvt_pk_bf16_f32 v250, v74, v75
	v_cvt_pk_bf16_f32 v251, v76, v77
	v_cvt_pk_bf16_f32 v252, v66, v67
	v_cvt_pk_bf16_f32 v253, v68, v69
	global_store_dwordx4 v[182:183], v[250:253], off sc1
	s_nop 1
	s_branch .Lgu_last_join
.LBB0_212:
	s_add_u32 s46, s44, 0xfffc0080
	s_addc_u32 s47, s45, -1
	s_add_i32 s84, 0, 0x10000
	s_cmp_eq_u32 s79, 12
	s_cselect_b32 s55, s12, s47
	s_cselect_b32 s54, s13, s46
	s_cselect_b32 s47, s17, s77
	s_cselect_b32 s46, s27, s76
	s_add_i32 s86, 0, 0x14000
	v_add_u32_e32 v154, s84, v148
	v_add_u32_e32 v170, s86, v148
	ds_read_b128 v[140:143], v154
	ds_read_b128 v[144:147], v154 offset:1024
	ds_read_b128 v[150:153], v154 offset:2048
	ds_read_b128 v[154:157], v154 offset:3072
	ds_read_b128 v[158:161], v170
	ds_read_b128 v[162:165], v170 offset:1024
	ds_read_b128 v[166:169], v170 offset:2048
	ds_read_b128 v[170:173], v170 offset:3072
	v_lshl_add_u64 v[178:179], s[44:45], 0, v[0:1]
	s_add_i32 m0, s38, 0xc000
	ds_read_b128 v[174:177], v149
	ds_read_b128 v[194:197], v149 offset:1024
	ds_read_b128 v[198:201], v149 offset:2048
	ds_read_b128 v[202:205], v149 offset:3072
	ds_read_b128 v[206:209], v149 offset:4096
	ds_read_b128 v[210:213], v149 offset:5120
	ds_read_b128 v[214:217], v149 offset:6144
	ds_read_b128 v[218:221], v149 offset:7168
	global_load_lds_dwordx4 v[178:179], off
	v_lshl_add_u64 v[178:179], s[44:45], 0, v[138:139]
	s_add_i32 m0, s38, 0xe000
	s_nop 0
	global_load_lds_dwordx4 v[178:179], off
	s_waitcnt vmcnt(8)
	s_waitcnt lgkmcnt(0)
	s_barrier
; #define PG8_STAGE(bufoff, gbase, voff) do { _Pragma("unroll") for (int _i = 0; _i < 2; ++_i) \
;         __builtin_amdgcn_global_load_lds((const unsigned*)((const char*)(gbase) + (voff)[_i]), (LAS unsigned*)(lds + (bufoff) + ldsw + _i * 8192), 16, 0, 0); } while (0)
; #define PG8_LDA(dst, b, h) do { _Pragma("unroll") for (int m = 0; m < 4; ++m) _Pragma("unroll") for (int k = 0; k < 2; ++k) dst[m][k] = *(const LAS bf16x8*)(lds + PG8_SA(b, h) + aoff + m * 2048 + k * 1024); } while (0)
; #define PG8_LDB(dst, b, h) do { _Pragma("unroll") for (int n = 0; n < 2; ++n) _Pragma("unroll") for (int k = 0; k < 2; ++k) dst[n][k] = *(const LAS bf16x8*)(lds + PG8_SB(b, h) + boff + n * 2048 + k * 1024); } while (0)
; #define PG8_MMA(ai, bj, At, Bt) do { __builtin_amdgcn_s_setprio(1); _Pragma("unroll") for (int m = 0; m < 4; ++m) _Pragma("unroll") for (int n = 0; n < 2; ++n) _Pragma("unroll") for (int k = 0; k < 2; ++k) \
;         acc[ai][bj][m][n] = __builtin_amdgcn_mfma_f32_16x16x32_bf16(Bt[n][k], At[m][k], acc[ai][bj][m][n], 0, 0, 0); __builtin_amdgcn_s_setprio(0); } while (0)
; #define PG8_WAIT_V(n) asm volatile("s_waitcnt vmcnt(" #n ")" ::: "memory")
; #define PG8_WAIT_L(n) asm volatile("s_waitcnt lgkmcnt(" #n ")" ::: "memory")
; #define PG8_BAR __builtin_amdgcn_s_barrier()
; #define PG8_SCHED __builtin_amdgcn_sched_barrier(0)
; template <class Epi, class Pre, bool AG = false>
; __device__ __forceinline__ void gemm_phase(LAS unsigned char* lds, const Gemm g, const StaticOrder& S, const Epi& E, const Pre& P) {
;     ...
;             PG8_LDB(B0, 0, 0); PG8_LDB(B1, 0, 1); PG8_SCHED; PG8_LDA(At, 0, 0); PG8_STAGE(PG8_SA(1, 1), a1 + hstepA, voffA);
;             PG8_WAIT_V(8); PG8_WAIT_L(0); PG8_BAR; PG8_MMA(0, 0, At, B0); PG8_MMA(0, 1, At, B1); PG8_BAR; PG8_SCHED;
;             PG8_LDA(At, 0, 1); PG8_STAGE(PG8_SB(0, 0), b2, voffB); PG8_STAGE(PG8_SB(0, 1), b2 + hstep, voffB); PG8_STAGE(PG8_SA(0, 0), a2, voffA);
;             PG8_WAIT_V(8); PG8_WAIT_L(0); PG8_BAR; PG8_MMA(1, 0, At, B0); PG8_MMA(1, 1, At, B1); PG8_BAR; PG8_SCHED;
;             PG8_LDB(B0, 1, 0); PG8_LDB(B1, 1, 1); PG8_SCHED; PG8_LDA(At, 1, 0); PG8_STAGE(PG8_SA(0, 1), a2 + hstepA, voffA);
;             PG8_WAIT_V(8); PG8_WAIT_L(0); PG8_BAR; PG8_MMA(0, 0, At, B0); PG8_MMA(0, 1, At, B1); PG8_BAR; PG8_SCHED;
	s_setprio 1
	v_mfma_f32_16x16x32_bf16 v[122:125], v[140:143], v[174:177], v[122:125]
	v_mfma_f32_16x16x32_bf16 v[114:117], v[150:153], v[174:177], v[114:117]
	v_mfma_f32_16x16x32_bf16 v[106:109], v[140:143], v[198:201], v[106:109]
	v_mfma_f32_16x16x32_bf16 v[98:101], v[150:153], v[198:201], v[98:101]
	v_mfma_f32_16x16x32_bf16 v[90:93], v[140:143], v[206:209], v[90:93]
	v_mfma_f32_16x16x32_bf16 v[82:85], v[150:153], v[206:209], v[82:85]
	v_mfma_f32_16x16x32_bf16 v[74:77], v[140:143], v[214:217], v[74:77]
	v_mfma_f32_16x16x32_bf16 v[66:69], v[150:153], v[214:217], v[66:69]
	v_mfma_f32_16x16x32_bf16 v[122:125], v[144:147], v[194:197], v[122:125]
	v_mfma_f32_16x16x32_bf16 v[114:117], v[154:157], v[194:197], v[114:117]
	v_mfma_f32_16x16x32_bf16 v[106:109], v[144:147], v[202:205], v[106:109]
	v_mfma_f32_16x16x32_bf16 v[98:101], v[154:157], v[202:205], v[98:101]
	v_mfma_f32_16x16x32_bf16 v[90:93], v[144:147], v[210:213], v[90:93]
	v_mfma_f32_16x16x32_bf16 v[82:85], v[154:157], v[210:213], v[82:85]
	v_mfma_f32_16x16x32_bf16 v[74:77], v[144:147], v[218:221], v[74:77]
	v_mfma_f32_16x16x32_bf16 v[66:69], v[154:157], v[218:221], v[66:69]
	v_mfma_f32_16x16x32_bf16 v[126:129], v[158:161], v[174:177], v[126:129]
	v_mfma_f32_16x16x32_bf16 v[118:121], v[166:169], v[174:177], v[118:121]
	v_mfma_f32_16x16x32_bf16 v[110:113], v[158:161], v[198:201], v[110:113]
	v_mfma_f32_16x16x32_bf16 v[102:105], v[166:169], v[198:201], v[102:105]
	v_mfma_f32_16x16x32_bf16 v[94:97], v[158:161], v[206:209], v[94:97]
	v_mfma_f32_16x16x32_bf16 v[86:89], v[166:169], v[206:209], v[86:89]
	v_mfma_f32_16x16x32_bf16 v[78:81], v[158:161], v[214:217], v[78:81]
	v_mfma_f32_16x16x32_bf16 v[70:73], v[166:169], v[214:217], v[70:73]
	v_mfma_f32_16x16x32_bf16 v[126:129], v[162:165], v[194:197], v[126:129]
	v_mfma_f32_16x16x32_bf16 v[118:121], v[170:173], v[194:197], v[118:121]
	v_mfma_f32_16x16x32_bf16 v[110:113], v[162:165], v[202:205], v[110:113]
	v_mfma_f32_16x16x32_bf16 v[102:105], v[170:173], v[202:205], v[102:105]
	v_mfma_f32_16x16x32_bf16 v[94:97], v[162:165], v[210:213], v[94:97]
	v_mfma_f32_16x16x32_bf16 v[86:89], v[170:173], v[210:213], v[86:89]
	v_mfma_f32_16x16x32_bf16 v[78:81], v[162:165], v[218:221], v[78:81]
	v_mfma_f32_16x16x32_bf16 v[70:73], v[170:173], v[218:221], v[70:73]
	s_setprio 0
	s_barrier
	s_add_i32 s84, s84, s31
	v_lshl_add_u64 v[178:179], s[46:47], 0, v[134:135]
	s_mov_b32 m0, s84
	ds_read_b128 v[174:177], v149 offset:16384
	ds_read_b128 v[194:197], v149 offset:17408
	ds_read_b128 v[198:201], v149 offset:18432
	ds_read_b128 v[202:205], v149 offset:19456
	ds_read_b128 v[206:209], v149 offset:20480
	ds_read_b128 v[210:213], v149 offset:21504
	ds_read_b128 v[214:217], v149 offset:22528
	ds_read_b128 v[218:221], v149 offset:23552
	global_load_lds_dwordx4 v[178:179], off
	s_add_i32 m0, s84, 0x2000
	s_add_u32 s84, s46, 0x40000
	v_lshl_add_u64 v[180:181], s[46:47], 0, v[130:131]
	s_addc_u32 s85, s47, 0
	s_add_i32 s86, s86, s31
	global_load_lds_dwordx4 v[180:181], off
	v_lshl_add_u64 v[182:183], s[84:85], 0, v[134:135]
	s_mov_b32 m0, s86
	v_lshl_add_u64 v[188:189], s[54:55], 0, v[132:133]
	global_load_lds_dwordx4 v[182:183], off
	v_lshl_add_u64 v[182:183], s[84:85], 0, v[130:131]
	s_add_i32 m0, s86, 0x2000
	s_nop 0
	global_load_lds_dwordx4 v[182:183], off
	v_lshl_add_u64 v[182:183], s[54:55], 0, v[136:137]
	s_mov_b32 m0, s38
	s_nop 0
	global_load_lds_dwordx4 v[182:183], off
	s_mov_b32 m0, s48
	s_nop 0
	global_load_lds_dwordx4 v[188:189], off
	s_waitcnt vmcnt(8)
	s_waitcnt lgkmcnt(0)
	s_barrier
	s_setprio 1
	v_mfma_f32_16x16x32_bf16 v[58:61], v[140:143], v[174:177], v[58:61]
	v_mfma_f32_16x16x32_bf16 v[50:53], v[150:153], v[174:177], v[50:53]
	v_mfma_f32_16x16x32_bf16 v[42:45], v[140:143], v[198:201], v[42:45]
	v_mfma_f32_16x16x32_bf16 v[34:37], v[150:153], v[198:201], v[34:37]
	v_mfma_f32_16x16x32_bf16 v[26:29], v[140:143], v[206:209], v[26:29]
	v_mfma_f32_16x16x32_bf16 v[18:21], v[150:153], v[206:209], v[18:21]
	v_mfma_f32_16x16x32_bf16 v[10:13], v[140:143], v[214:217], v[10:13]
	v_mfma_f32_16x16x32_bf16 v[6:9], v[150:153], v[214:217], v[6:9]
	v_mfma_f32_16x16x32_bf16 v[58:61], v[144:147], v[194:197], v[58:61]
	v_mfma_f32_16x16x32_bf16 v[50:53], v[154:157], v[194:197], v[50:53]
	v_mfma_f32_16x16x32_bf16 v[42:45], v[144:147], v[202:205], v[42:45]
	v_mfma_f32_16x16x32_bf16 v[34:37], v[154:157], v[202:205], v[34:37]
	v_mfma_f32_16x16x32_bf16 v[26:29], v[144:147], v[210:213], v[26:29]
	v_mfma_f32_16x16x32_bf16 v[18:21], v[154:157], v[210:213], v[18:21]
	v_mfma_f32_16x16x32_bf16 v[10:13], v[144:147], v[218:221], v[10:13]
	v_mfma_f32_16x16x32_bf16 v[6:9], v[154:157], v[218:221], v[6:9]
	v_mfma_f32_16x16x32_bf16 v[62:65], v[158:161], v[174:177], v[62:65]
	v_mfma_f32_16x16x32_bf16 v[54:57], v[166:169], v[174:177], v[54:57]
	v_mfma_f32_16x16x32_bf16 v[46:49], v[158:161], v[198:201], v[46:49]
	v_mfma_f32_16x16x32_bf16 v[38:41], v[166:169], v[198:201], v[38:41]
	v_mfma_f32_16x16x32_bf16 v[30:33], v[158:161], v[206:209], v[30:33]
	v_mfma_f32_16x16x32_bf16 v[22:25], v[166:169], v[206:209], v[22:25]
	v_mfma_f32_16x16x32_bf16 v[14:17], v[158:161], v[214:217], v[14:17]
	v_mfma_f32_16x16x32_bf16 v[2:5], v[166:169], v[214:217], v[2:5]
	v_mfma_f32_16x16x32_bf16 v[62:65], v[162:165], v[194:197], v[62:65]
	v_mfma_f32_16x16x32_bf16 v[54:57], v[170:173], v[194:197], v[54:57]
	v_mfma_f32_16x16x32_bf16 v[46:49], v[162:165], v[202:205], v[46:49]
	v_mfma_f32_16x16x32_bf16 v[38:41], v[170:173], v[202:205], v[38:41]
	v_mfma_f32_16x16x32_bf16 v[30:33], v[162:165], v[210:213], v[30:33]
	v_mfma_f32_16x16x32_bf16 v[22:25], v[170:173], v[210:213], v[22:25]
	v_mfma_f32_16x16x32_bf16 v[14:17], v[162:165], v[218:221], v[14:17]
	v_mfma_f32_16x16x32_bf16 v[2:5], v[170:173], v[218:221], v[2:5]
	s_setprio 0
	s_barrier
; #define PG8_STAGE(bufoff, gbase, voff) do { _Pragma("unroll") for (int _i = 0; _i < 2; ++_i) \
;         __builtin_amdgcn_global_load_lds((const unsigned*)((const char*)(gbase) + (voff)[_i]), (LAS unsigned*)(lds + (bufoff) + ldsw + _i * 8192), 16, 0, 0); } while (0)
; #define PG8_LDA(dst, b, h) do { _Pragma("unroll") for (int m = 0; m < 4; ++m) _Pragma("unroll") for (int k = 0; k < 2; ++k) dst[m][k] = *(const LAS bf16x8*)(lds + PG8_SA(b, h) + aoff + m * 2048 + k * 1024); } while (0)
; #define PG8_LDB(dst, b, h) do { _Pragma("unroll") for (int n = 0; n < 2; ++n) _Pragma("unroll") for (int k = 0; k < 2; ++k) dst[n][k] = *(const LAS bf16x8*)(lds + PG8_SB(b, h) + boff + n * 2048 + k * 1024); } while (0)
; #define PG8_MMA(ai, bj, At, Bt) do { __builtin_amdgcn_s_setprio(1); _Pragma("unroll") for (int m = 0; m < 4; ++m) _Pragma("unroll") for (int n = 0; n < 2; ++n) _Pragma("unroll") for (int k = 0; k < 2; ++k) \
;         acc[ai][bj][m][n] = __builtin_amdgcn_mfma_f32_16x16x32_bf16(Bt[n][k], At[m][k], acc[ai][bj][m][n], 0, 0, 0); __builtin_amdgcn_s_setprio(0); } while (0)
; #define PG8_WAIT_V(n) asm volatile("s_waitcnt vmcnt(" #n ")" ::: "memory")
; #define PG8_WAIT_L(n) asm volatile("s_waitcnt lgkmcnt(" #n ")" ::: "memory")
; #define PG8_BAR __builtin_amdgcn_s_barrier()
; #define PG8_SCHED __builtin_amdgcn_sched_barrier(0)
; template <class Epi, class Pre, bool AG = false>
; __device__ __forceinline__ void gemm_phase(LAS unsigned char* lds, const Gemm g, const StaticOrder& S, const Epi& E, const Pre& P) {
;     ...
;             PG8_LDB(B0, 1, 0); PG8_LDB(B1, 1, 1); PG8_SCHED; PG8_LDA(At, 1, 0); PG8_STAGE(PG8_SA(0, 1), a2 + hstepA, voffA);
;             PG8_WAIT_V(8); PG8_WAIT_L(0); PG8_BAR; PG8_MMA(0, 0, At, B0); PG8_MMA(0, 1, At, B1); PG8_BAR; PG8_SCHED;
;             PG8_LDA(At, 1, 1); PG8_STAGE(PG8_SB(1, 0), b3, voffB); PG8_STAGE(PG8_SB(1, 1), b3 + hstep, voffB); PG8_STAGE(PG8_SA(1, 0), a3, voffA);
;             PG8_WAIT_V(8); PG8_WAIT_L(0); PG8_BAR; PG8_MMA(1, 0, At, B0); PG8_MMA(1, 1, At, B1); PG8_BAR; PG8_SCHED;
	s_add_i32 s84, 0, 0x18000
	s_add_i32 s85, 0, 0x1c000
	v_add_u32_e32 v154, s84, v148
	v_add_u32_e32 v170, s85, v148
	ds_read_b128 v[140:143], v154
	ds_read_b128 v[144:147], v154 offset:1024
	ds_read_b128 v[150:153], v154 offset:2048
	ds_read_b128 v[154:157], v154 offset:3072
	ds_read_b128 v[158:161], v170
	ds_read_b128 v[162:165], v170 offset:1024
	ds_read_b128 v[166:169], v170 offset:2048
	ds_read_b128 v[170:173], v170 offset:3072
	s_add_u32 s54, s54, 0x40000
	s_addc_u32 s55, s55, 0
	s_mov_b32 m0, s49
	v_lshl_add_u64 v[190:191], s[54:55], 0, v[136:137]
	ds_read_b128 v[174:177], v149 offset:32768
	ds_read_b128 v[194:197], v149 offset:33792
	ds_read_b128 v[198:201], v149 offset:34816
	ds_read_b128 v[202:205], v149 offset:35840
	ds_read_b128 v[206:209], v149 offset:36864
	ds_read_b128 v[210:213], v149 offset:37888
	ds_read_b128 v[214:217], v149 offset:38912
	ds_read_b128 v[218:221], v149 offset:39936
	global_load_lds_dwordx4 v[190:191], off
	v_lshl_add_u64 v[190:191], s[54:55], 0, v[132:133]
	s_mov_b32 m0, s53
	s_nop 0
	global_load_lds_dwordx4 v[190:191], off
	s_waitcnt vmcnt(8)
	s_waitcnt lgkmcnt(0)
	s_barrier
	s_setprio 1
	v_mfma_f32_16x16x32_bf16 v[122:125], v[140:143], v[174:177], v[122:125]
	v_mfma_f32_16x16x32_bf16 v[114:117], v[150:153], v[174:177], v[114:117]
	v_mfma_f32_16x16x32_bf16 v[106:109], v[140:143], v[198:201], v[106:109]
	v_mfma_f32_16x16x32_bf16 v[98:101], v[150:153], v[198:201], v[98:101]
	v_mfma_f32_16x16x32_bf16 v[90:93], v[140:143], v[206:209], v[90:93]
	v_mfma_f32_16x16x32_bf16 v[82:85], v[150:153], v[206:209], v[82:85]
	v_mfma_f32_16x16x32_bf16 v[74:77], v[140:143], v[214:217], v[74:77]
	v_mfma_f32_16x16x32_bf16 v[66:69], v[150:153], v[214:217], v[66:69]
	v_mfma_f32_16x16x32_bf16 v[122:125], v[144:147], v[194:197], v[122:125]
	v_mfma_f32_16x16x32_bf16 v[114:117], v[154:157], v[194:197], v[114:117]
	v_mfma_f32_16x16x32_bf16 v[106:109], v[144:147], v[202:205], v[106:109]
	v_mfma_f32_16x16x32_bf16 v[98:101], v[154:157], v[202:205], v[98:101]
	v_mfma_f32_16x16x32_bf16 v[90:93], v[144:147], v[210:213], v[90:93]
	v_mfma_f32_16x16x32_bf16 v[82:85], v[154:157], v[210:213], v[82:85]
	v_mfma_f32_16x16x32_bf16 v[74:77], v[144:147], v[218:221], v[74:77]
	v_mfma_f32_16x16x32_bf16 v[66:69], v[154:157], v[218:221], v[66:69]
	v_mfma_f32_16x16x32_bf16 v[126:129], v[158:161], v[174:177], v[126:129]
	v_mfma_f32_16x16x32_bf16 v[118:121], v[166:169], v[174:177], v[118:121]
	v_mfma_f32_16x16x32_bf16 v[110:113], v[158:161], v[198:201], v[110:113]
	v_mfma_f32_16x16x32_bf16 v[102:105], v[166:169], v[198:201], v[102:105]
	v_mfma_f32_16x16x32_bf16 v[94:97], v[158:161], v[206:209], v[94:97]
	v_mfma_f32_16x16x32_bf16 v[86:89], v[166:169], v[206:209], v[86:89]
	v_mfma_f32_16x16x32_bf16 v[78:81], v[158:161], v[214:217], v[78:81]
	v_mfma_f32_16x16x32_bf16 v[70:73], v[166:169], v[214:217], v[70:73]
	v_mfma_f32_16x16x32_bf16 v[126:129], v[162:165], v[194:197], v[126:129]
	v_mfma_f32_16x16x32_bf16 v[118:121], v[170:173], v[194:197], v[118:121]
	v_mfma_f32_16x16x32_bf16 v[110:113], v[162:165], v[202:205], v[110:113]
	v_mfma_f32_16x16x32_bf16 v[102:105], v[170:173], v[202:205], v[102:105]
	v_mfma_f32_16x16x32_bf16 v[94:97], v[162:165], v[210:213], v[94:97]
	v_mfma_f32_16x16x32_bf16 v[86:89], v[170:173], v[210:213], v[86:89]
	v_mfma_f32_16x16x32_bf16 v[78:81], v[162:165], v[218:221], v[78:81]
	v_mfma_f32_16x16x32_bf16 v[70:73], v[170:173], v[218:221], v[70:73]
	s_setprio 0
	s_barrier
	s_add_i32 s54, s84, s31
	v_lshl_add_u64 v[178:179], v[178:179], 0, s[66:67]
	s_mov_b32 m0, s54
	ds_read_b128 v[174:177], v149 offset:49152
	ds_read_b128 v[194:197], v149 offset:50176
	ds_read_b128 v[198:201], v149 offset:51200
	ds_read_b128 v[202:205], v149 offset:52224
	ds_read_b128 v[206:209], v149 offset:53248
	ds_read_b128 v[210:213], v149 offset:54272
	ds_read_b128 v[214:217], v149 offset:55296
	ds_read_b128 v[218:221], v149 offset:56320
	global_load_lds_dwordx4 v[178:179], off
	s_add_i32 m0, s54, 0x2000
	s_add_u32 s46, s46, 0x40080
	v_lshl_add_u64 v[178:179], v[180:181], 0, s[66:67]
	s_addc_u32 s47, s47, 0
	s_add_i32 s54, s85, s31
	global_load_lds_dwordx4 v[178:179], off
	v_lshl_add_u64 v[178:179], s[46:47], 0, v[134:135]
	s_mov_b32 m0, s54
	s_nop 0
	global_load_lds_dwordx4 v[178:179], off
	v_lshl_add_u64 v[178:179], s[46:47], 0, v[130:131]
	s_add_i32 m0, s54, 0x2000
	s_nop 0
	global_load_lds_dwordx4 v[178:179], off
	v_lshl_add_u64 v[178:179], v[182:183], 0, s[66:67]
	s_mov_b32 m0, s58
	s_nop 0
	global_load_lds_dwordx4 v[178:179], off
	v_lshl_add_u64 v[178:179], v[188:189], 0, s[66:67]
	s_mov_b32 m0, s59
	s_nop 0
	global_load_lds_dwordx4 v[178:179], off
	s_waitcnt vmcnt(8)
	s_waitcnt lgkmcnt(0)
	s_barrier
	s_setprio 1
	s_cmp_eq_u32 s79, 12
	s_cbranch_scc1 .Lgu_last_sp2
	v_mfma_f32_16x16x32_bf16 v[58:61], v[140:143], v[174:177], v[58:61]
	v_mfma_f32_16x16x32_bf16 v[50:53], v[150:153], v[174:177], v[50:53]
	v_mfma_f32_16x16x32_bf16 v[42:45], v[140:143], v[198:201], v[42:45]
	v_mfma_f32_16x16x32_bf16 v[34:37], v[150:153], v[198:201], v[34:37]
	v_mfma_f32_16x16x32_bf16 v[26:29], v[140:143], v[206:209], v[26:29]
	v_mfma_f32_16x16x32_bf16 v[18:21], v[150:153], v[206:209], v[18:21]
	v_mfma_f32_16x16x32_bf16 v[10:13], v[140:143], v[214:217], v[10:13]
	v_mfma_f32_16x16x32_bf16 v[6:9], v[150:153], v[214:217], v[6:9]
	v_mfma_f32_16x16x32_bf16 v[58:61], v[144:147], v[194:197], v[58:61]
	v_mfma_f32_16x16x32_bf16 v[50:53], v[154:157], v[194:197], v[50:53]
	v_mfma_f32_16x16x32_bf16 v[42:45], v[144:147], v[202:205], v[42:45]
	v_mfma_f32_16x16x32_bf16 v[34:37], v[154:157], v[202:205], v[34:37]
	v_mfma_f32_16x16x32_bf16 v[26:29], v[144:147], v[210:213], v[26:29]
	v_mfma_f32_16x16x32_bf16 v[18:21], v[154:157], v[210:213], v[18:21]
	v_mfma_f32_16x16x32_bf16 v[10:13], v[144:147], v[218:221], v[10:13]
	v_mfma_f32_16x16x32_bf16 v[6:9], v[154:157], v[218:221], v[6:9]
	v_mfma_f32_16x16x32_bf16 v[62:65], v[158:161], v[174:177], v[62:65]
	v_mfma_f32_16x16x32_bf16 v[54:57], v[166:169], v[174:177], v[54:57]
	v_mfma_f32_16x16x32_bf16 v[46:49], v[158:161], v[198:201], v[46:49]
	v_mfma_f32_16x16x32_bf16 v[38:41], v[166:169], v[198:201], v[38:41]
	v_mfma_f32_16x16x32_bf16 v[30:33], v[158:161], v[206:209], v[30:33]
	v_mfma_f32_16x16x32_bf16 v[22:25], v[166:169], v[206:209], v[22:25]
	v_mfma_f32_16x16x32_bf16 v[14:17], v[158:161], v[214:217], v[14:17]
	v_mfma_f32_16x16x32_bf16 v[2:5], v[166:169], v[214:217], v[2:5]
	v_mfma_f32_16x16x32_bf16 v[62:65], v[162:165], v[194:197], v[62:65]
	v_mfma_f32_16x16x32_bf16 v[54:57], v[170:173], v[194:197], v[54:57]
	v_mfma_f32_16x16x32_bf16 v[46:49], v[162:165], v[202:205], v[46:49]
	v_mfma_f32_16x16x32_bf16 v[38:41], v[170:173], v[202:205], v[38:41]
	v_mfma_f32_16x16x32_bf16 v[30:33], v[162:165], v[210:213], v[30:33]
	v_mfma_f32_16x16x32_bf16 v[22:25], v[170:173], v[210:213], v[22:25]
	v_mfma_f32_16x16x32_bf16 v[14:17], v[162:165], v[218:221], v[14:17]
	v_mfma_f32_16x16x32_bf16 v[2:5], v[170:173], v[218:221], v[2:5]
; #define PG8_STAGE(bufoff, gbase, voff) do { _Pragma("unroll") for (int _i = 0; _i < 2; ++_i) \
;         __builtin_amdgcn_global_load_lds((const unsigned*)((const char*)(gbase) + (voff)[_i]), (LAS unsigned*)(lds + (bufoff) + ldsw + _i * 8192), 16, 0, 0); } while (0)
; #define PG8_LDA(dst, b, h) do { _Pragma("unroll") for (int m = 0; m < 4; ++m) _Pragma("unroll") for (int k = 0; k < 2; ++k) dst[m][k] = *(const LAS bf16x8*)(lds + PG8_SA(b, h) + aoff + m * 2048 + k * 1024); } while (0)
; #define PG8_LDB(dst, b, h) do { _Pragma("unroll") for (int n = 0; n < 2; ++n) _Pragma("unroll") for (int k = 0; k < 2; ++k) dst[n][k] = *(const LAS bf16x8*)(lds + PG8_SB(b, h) + boff + n * 2048 + k * 1024); } while (0)
; template <class Epi, class Pre, bool AG = false>
; __device__ __forceinline__ void gemm_phase(LAS unsigned char* lds, const Gemm g, const StaticOrder& S, const Epi& E, const Pre& P) {
;     ...
;         for (int t = 0; t < nt; t += 2) {
;             const bool last = (t == nt - 2);
;             const char* a1 = cA + (size_t)(t + 1) * kstepA;
;             const char* a2 = last ? nA : cA + (size_t)(t + 2) * kstepA; const char* b2 = last ? nB : cB + (size_t)(t + 2) * kstep;
;             const char* a3 = a2 + kstepA; const char* b3 = b2 + kstep;
;             if constexpr (Epi::MIDK) { if (t == E.midk_t) E.mid(acc, cur, ui, wr, wc, fr, fq); }
;             PG8_LDB(B0, 0, 0); PG8_LDB(B1, 0, 1); PG8_SCHED; PG8_LDA(At, 0, 0); PG8_STAGE(PG8_SA(1, 1), a1 + hstepA, voffA);
;             PG8_WAIT_V(8); PG8_WAIT_L(0); PG8_BAR; PG8_MMA(0, 0, At, B0); PG8_MMA(0, 1, At, B1); PG8_BAR; PG8_SCHED;
;             PG8_LDA(At, 0, 1); PG8_STAGE(PG8_SB(0, 0), b2, voffB); PG8_STAGE(PG8_SB(0, 1), b2 + hstep, voffB); PG8_STAGE(PG8_SA(0, 0), a2, voffA);
;             PG8_WAIT_V(8); PG8_WAIT_L(0); PG8_BAR; PG8_MMA(1, 0, At, B0); PG8_MMA(1, 1, At, B1); PG8_BAR; PG8_SCHED;
;             PG8_LDB(B0, 1, 0); PG8_LDB(B1, 1, 1); PG8_SCHED; PG8_LDA(At, 1, 0); PG8_STAGE(PG8_SA(0, 1), a2 + hstepA, voffA);
;             PG8_WAIT_V(8); PG8_WAIT_L(0); PG8_BAR; PG8_MMA(0, 0, At, B0); PG8_MMA(0, 1, At, B1); PG8_BAR; PG8_SCHED;
;             PG8_LDA(At, 1, 1); PG8_STAGE(PG8_SB(1, 0), b3, voffB); PG8_STAGE(PG8_SB(1, 1), b3 + hstep, voffB); PG8_STAGE(PG8_SA(1, 0), a3, voffA);
;             PG8_WAIT_V(8); PG8_WAIT_L(0); PG8_BAR; PG8_MMA(1, 0, At, B0); PG8_MMA(1, 1, At, B1); PG8_BAR; PG8_SCHED;
;         }
.Lgu_last_join:
	s_setprio 0
	s_barrier
	s_add_i32 s79, s79, 2
	s_add_u32 s44, s44, 0x100
	s_addc_u32 s45, s45, 0
	s_add_u32 s76, s76, 0x100
	s_addc_u32 s77, s77, 0
	s_cmp_gt_u32 s79, 13
	s_cbranch_scc0 .LBB0_212

;     __device__ __forceinline__ void operator()(const AccT& acc, const pg8::Unit& u, int ui, int wr, int wc, int fr, int fq) const {
;         const int row0 = u.pm * 256 + wr * 64 + fr, col0 = u.pn * 128 + wc * 32 + 8 * fq;
;         float rs[2][4]; lane_rstd(lds, ui, wr, fr, rs);
; #pragma unroll
;         for (int ai = 0; ai < 2; ++ai)
; #pragma unroll
;             for (int m = 0; m < 4; ++m) {
;                 const float s = rs[ai][m]; u16* op = act + (size_t)(row0 + ai * 128 + m * 16) * FF + col0;
;                 const float c1 = -1.4426950408889634f * s, c2 = s * s;
.LBB0_215:
	v_and_b32_e32 v141, 15, v234
	s_lshl_b32 s12, s71, 8
	s_add_i32 s12, s12, s56
	v_or_b32_e32 v150, s12, v141
	s_lshl_b32 s12, s62, 7
	v_lshrrev_b32_e32 v140, 1, v234
	v_and_or_b32 v140, v140, 24, s12
	v_or_b32_e32 v152, s57, v140
	s_lshl_b32 s12, s70, 10
	s_add_i32 s12, s60, s12
	v_lshl_add_u32 v140, v141, 2, s12
	ds_read2_b32 v[198:199], v140 offset0:128 offset1:144
	ds_read2_b32 v[200:201], v140 offset0:160 offset1:176
	v_ashrrev_i32_e32 v153, 31, v152
	v_mov_b64_e32 v[142:143], s[8:9]
	v_mad_i64_i32 v[156:157], s[12:13], v150, s37, v[142:143]
	v_lshlrev_b64 v[152:153], 1, v[152:153]
	s_mov_b32 s12, 0xb0000
	s_mov_b32 s13, 0
	v_lshl_add_u64 v[156:157], v[156:157], 0, v[152:153]
	v_lshl_add_u64 v[154:155], v[156:157], 0, s[12:13]
	s_mov_b32 s12, 0x16000
	s_andn2_b64 vcc, exec, s[6:7]
	s_waitcnt lgkmcnt(0)
; __device__ __forceinline__ unsigned pk2(float lo, float hi) { unsigned r; asm("v_cvt_pk_bf16_f32 %0, %1, %2" : "=v"(r) : "v"(lo), "v"(hi)); return r; }
; __device__ __forceinline__ void st16_wt(void* p, u32x4 v) { asm volatile("global_store_dwordx4 %0, %1, off sc1\n\ts_nop 1" :: "v"(p), "v"(v) : "memory"); }
; #define PG8_BAR __builtin_amdgcn_s_barrier()
; template <class Epi, class Pre, bool AG = false>
; __device__ __forceinline__ void gemm_phase(LAS unsigned char* lds, const Gemm g, const StaticOrder& S, const Epi& E, const Pre& P) {
;     ...
;         if (!has_next) break;
; #pragma unroll
;         for (int a = 0; a < 2; ++a)
; #pragma unroll
;             for (int b = 0; b < 2; ++b)
; #pragma unroll
;                 for (int m = 0; m < 4; ++m)
; #pragma unroll
;                     for (int n = 0; n < 2; ++n) acc[a][b][m][n] = (f32x4){0.f, 0.f, 0.f, 0.f};
;         cur = nxt; cA = nA; cB = nB; ++ui;
;         if (wr == 1) PG8_BAR;
;     __device__ __forceinline__ void operator()(const AccT& acc, const pg8::Unit& u, int ui, int wr, int wc, int fr, int fq) const {
;     ...
;             for (int m = 0; m < 4; ++m) {
;                 const float s = rs[ai][m]; u16* op = act + (size_t)(row0 + ai * 128 + m * 16) * FF + col0;
;                 const float c1 = -1.4426950408889634f * s, c2 = s * s;
;                 u32x4 w;
; #pragma unroll
;                 for (int n = 0; n < 2; ++n)
; #pragma unroll
;                     for (int hh = 0; hh < 2; ++hh) {
;                         const f32x2 ga = {acc[ai][0][m][n][2 * hh], acc[ai][0][m][n][2 * hh + 1]}, ua = {acc[ai][1][m][n][2 * hh], acc[ai][1][m][n][2 * hh + 1]};
;                         f32x2 t = ga * c1; t.x = fminf(t.x, 60.0f); t.y = fminf(t.y, 60.0f);
;                         f32x2 e; e.x = __builtin_amdgcn_exp2f(t.x); e.y = __builtin_amdgcn_exp2f(t.y);
;                         const f32x2 d = e + 1.0f;
;                         const float rp = __builtin_amdgcn_rcpf(d.x * d.y);
;                         const f32x2 r = {d.y * rp, d.x * rp};
;                         const f32x2 o = ((ga * ua) * c2) * r;
;                         w[2 * n + hh] = pk2(o.x, o.y);
;                     }
;                 st16_wt(op, w);
;             }
	v_mul_f32_e32 v158, 0xbfb8aa3b, v198
	v_mul_f32_e32 v161, v198, v198
	v_rcp_f32_e32 v160, v161
	v_pk_mul_f32 v[162:163], v[58:59], v[158:159] op_sel_hi:[1,0]
	v_pk_mul_f32 v[164:165], v[60:61], v[158:159] op_sel_hi:[1,0]
	v_pk_mul_f32 v[166:167], v[50:51], v[158:159] op_sel_hi:[1,0]
	v_pk_mul_f32 v[168:169], v[52:53], v[158:159] op_sel_hi:[1,0]
	v_exp_f32_e32 v162, v162
	v_exp_f32_e32 v163, v163
	v_exp_f32_e32 v164, v164
	v_exp_f32_e32 v165, v165
	v_exp_f32_e32 v166, v166
	v_exp_f32_e32 v167, v167
	v_exp_f32_e32 v168, v168
	v_exp_f32_e32 v169, v169
	v_pk_fma_f32 v[162:163], v[162:163], v[160:161], v[160:161] op_sel_hi:[1,0,0]
	v_pk_fma_f32 v[164:165], v[164:165], v[160:161], v[160:161] op_sel_hi:[1,0,0]
	v_pk_fma_f32 v[166:167], v[166:167], v[160:161], v[160:161] op_sel_hi:[1,0,0]
	v_pk_fma_f32 v[168:169], v[168:169], v[160:161], v[160:161] op_sel_hi:[1,0,0]
	v_pk_mul_f32 v[58:59], v[58:59], v[62:63]
	v_pk_mul_f32 v[60:61], v[60:61], v[64:65]
	v_pk_mul_f32 v[50:51], v[50:51], v[54:55]
	v_pk_mul_f32 v[52:53], v[52:53], v[56:57]
	v_rcp_f32_e32 v162, v162
	v_rcp_f32_e32 v163, v163
	v_rcp_f32_e32 v164, v164
	v_rcp_f32_e32 v165, v165
	v_rcp_f32_e32 v166, v166
	v_rcp_f32_e32 v167, v167
	v_rcp_f32_e32 v168, v168
	v_rcp_f32_e32 v169, v169
	s_nop 0
	v_pk_mul_f32 v[58:59], v[58:59], v[162:163]
	v_pk_mul_f32 v[60:61], v[60:61], v[164:165]
	v_pk_mul_f32 v[50:51], v[50:51], v[166:167]
	v_pk_mul_f32 v[52:53], v[52:53], v[168:169]
	v_cvt_pk_bf16_f32 v170, v58, v59
	v_cvt_pk_bf16_f32 v171, v60, v61
	v_cvt_pk_bf16_f32 v172, v50, v51
	v_cvt_pk_bf16_f32 v173, v52, v53
	global_store_dwordx4 v[154:155], v[170:173], off sc1
	s_nop 1
	v_lshl_add_u64 v[154:155], v[154:155], 0, s[12:13]
	v_mul_f32_e32 v158, 0xbfb8aa3b, v199
	v_mul_f32_e32 v161, v199, v199
	v_rcp_f32_e32 v160, v161
	v_pk_mul_f32 v[162:163], v[42:43], v[158:159] op_sel_hi:[1,0]
	v_pk_mul_f32 v[164:165], v[44:45], v[158:159] op_sel_hi:[1,0]
	v_pk_mul_f32 v[166:167], v[34:35], v[158:159] op_sel_hi:[1,0]
	v_pk_mul_f32 v[168:169], v[36:37], v[158:159] op_sel_hi:[1,0]
	v_exp_f32_e32 v162, v162
	v_exp_f32_e32 v163, v163
	v_exp_f32_e32 v164, v164
	v_exp_f32_e32 v165, v165
	v_exp_f32_e32 v166, v166
	v_exp_f32_e32 v167, v167
	v_exp_f32_e32 v168, v168
	v_exp_f32_e32 v169, v169
	v_pk_fma_f32 v[162:163], v[162:163], v[160:161], v[160:161] op_sel_hi:[1,0,0]
	v_pk_fma_f32 v[164:165], v[164:165], v[160:161], v[160:161] op_sel_hi:[1,0,0]
	v_pk_fma_f32 v[166:167], v[166:167], v[160:161], v[160:161] op_sel_hi:[1,0,0]
	v_pk_fma_f32 v[168:169], v[168:169], v[160:161], v[160:161] op_sel_hi:[1,0,0]
	v_pk_mul_f32 v[42:43], v[42:43], v[46:47]
	v_pk_mul_f32 v[44:45], v[44:45], v[48:49]
	v_pk_mul_f32 v[34:35], v[34:35], v[38:39]
	v_pk_mul_f32 v[36:37], v[36:37], v[40:41]
	v_rcp_f32_e32 v162, v162
	v_rcp_f32_e32 v163, v163
	v_rcp_f32_e32 v164, v164
	v_rcp_f32_e32 v165, v165
	v_rcp_f32_e32 v166, v166
	v_rcp_f32_e32 v167, v167
	v_rcp_f32_e32 v168, v168
	v_rcp_f32_e32 v169, v169
	s_nop 0
	v_pk_mul_f32 v[42:43], v[42:43], v[162:163]
	v_pk_mul_f32 v[44:45], v[44:45], v[164:165]
	v_pk_mul_f32 v[34:35], v[34:35], v[166:167]
	v_pk_mul_f32 v[36:37], v[36:37], v[168:169]
	v_cvt_pk_bf16_f32 v174, v42, v43
	v_cvt_pk_bf16_f32 v175, v44, v45
	v_cvt_pk_bf16_f32 v176, v34, v35
	v_cvt_pk_bf16_f32 v177, v36, v37
	global_store_dwordx4 v[154:155], v[174:177], off sc1
	s_nop 1
	v_lshl_add_u64 v[154:155], v[154:155], 0, s[12:13]
	v_mul_f32_e32 v158, 0xbfb8aa3b, v200
	v_mul_f32_e32 v161, v200, v200
	v_rcp_f32_e32 v160, v161
	v_pk_mul_f32 v[162:163], v[26:27], v[158:159] op_sel_hi:[1,0]
	v_pk_mul_f32 v[164:165], v[28:29], v[158:159] op_sel_hi:[1,0]
	v_pk_mul_f32 v[166:167], v[18:19], v[158:159] op_sel_hi:[1,0]
	v_pk_mul_f32 v[168:169], v[20:21], v[158:159] op_sel_hi:[1,0]
	v_exp_f32_e32 v162, v162
	v_exp_f32_e32 v163, v163
	v_exp_f32_e32 v164, v164
	v_exp_f32_e32 v165, v165
	v_exp_f32_e32 v166, v166
	v_exp_f32_e32 v167, v167
	v_exp_f32_e32 v168, v168
	v_exp_f32_e32 v169, v169
	v_pk_fma_f32 v[162:163], v[162:163], v[160:161], v[160:161] op_sel_hi:[1,0,0]
	v_pk_fma_f32 v[164:165], v[164:165], v[160:161], v[160:161] op_sel_hi:[1,0,0]
	v_pk_fma_f32 v[166:167], v[166:167], v[160:161], v[160:161] op_sel_hi:[1,0,0]
	v_pk_fma_f32 v[168:169], v[168:169], v[160:161], v[160:161] op_sel_hi:[1,0,0]
	v_pk_mul_f32 v[26:27], v[26:27], v[30:31]
	v_pk_mul_f32 v[28:29], v[28:29], v[32:33]
	v_pk_mul_f32 v[18:19], v[18:19], v[22:23]
	v_pk_mul_f32 v[20:21], v[20:21], v[24:25]
	v_rcp_f32_e32 v162, v162
	v_rcp_f32_e32 v163, v163
	v_rcp_f32_e32 v164, v164
	v_rcp_f32_e32 v165, v165
	v_rcp_f32_e32 v166, v166
	v_rcp_f32_e32 v167, v167
	v_rcp_f32_e32 v168, v168
	v_rcp_f32_e32 v169, v169
	s_nop 0
	v_pk_mul_f32 v[26:27], v[26:27], v[162:163]
	v_pk_mul_f32 v[28:29], v[28:29], v[164:165]
	v_pk_mul_f32 v[18:19], v[18:19], v[166:167]
	v_pk_mul_f32 v[20:21], v[20:21], v[168:169]
	v_cvt_pk_bf16_f32 v170, v26, v27
	v_cvt_pk_bf16_f32 v171, v28, v29
	v_cvt_pk_bf16_f32 v172, v18, v19
	v_cvt_pk_bf16_f32 v173, v20, v21
	global_store_dwordx4 v[154:155], v[170:173], off sc1
	s_nop 1
	v_lshl_add_u64 v[154:155], v[154:155], 0, s[12:13]
	v_mul_f32_e32 v158, 0xbfb8aa3b, v201
	v_mul_f32_e32 v161, v201, v201
	v_rcp_f32_e32 v160, v161
	v_pk_mul_f32 v[162:163], v[10:11], v[158:159] op_sel_hi:[1,0]
	v_pk_mul_f32 v[164:165], v[12:13], v[158:159] op_sel_hi:[1,0]
	v_pk_mul_f32 v[166:167], v[6:7], v[158:159] op_sel_hi:[1,0]
	v_pk_mul_f32 v[168:169], v[8:9], v[158:159] op_sel_hi:[1,0]
	v_exp_f32_e32 v162, v162
	v_exp_f32_e32 v163, v163
	v_exp_f32_e32 v164, v164
	v_exp_f32_e32 v165, v165
	v_exp_f32_e32 v166, v166
	v_exp_f32_e32 v167, v167
	v_exp_f32_e32 v168, v168
	v_exp_f32_e32 v169, v169
	v_pk_fma_f32 v[162:163], v[162:163], v[160:161], v[160:161] op_sel_hi:[1,0,0]
	v_pk_fma_f32 v[164:165], v[164:165], v[160:161], v[160:161] op_sel_hi:[1,0,0]
	v_pk_fma_f32 v[166:167], v[166:167], v[160:161], v[160:161] op_sel_hi:[1,0,0]
	v_pk_fma_f32 v[168:169], v[168:169], v[160:161], v[160:161] op_sel_hi:[1,0,0]
	v_pk_mul_f32 v[10:11], v[10:11], v[14:15]
	v_pk_mul_f32 v[12:13], v[12:13], v[16:17]
	v_pk_mul_f32 v[6:7], v[6:7], v[2:3]
	v_pk_mul_f32 v[8:9], v[8:9], v[4:5]
	v_rcp_f32_e32 v162, v162
	v_rcp_f32_e32 v163, v163
	v_rcp_f32_e32 v164, v164
	v_rcp_f32_e32 v165, v165
	v_rcp_f32_e32 v166, v166
	v_rcp_f32_e32 v167, v167
	v_rcp_f32_e32 v168, v168
	v_rcp_f32_e32 v169, v169
	s_nop 0
	v_pk_mul_f32 v[10:11], v[10:11], v[162:163]
	v_pk_mul_f32 v[12:13], v[12:13], v[164:165]
	v_pk_mul_f32 v[6:7], v[6:7], v[166:167]
	v_pk_mul_f32 v[8:9], v[8:9], v[168:169]
	v_cvt_pk_bf16_f32 v174, v10, v11
	v_cvt_pk_bf16_f32 v175, v12, v13
	v_cvt_pk_bf16_f32 v176, v6, v7
	v_cvt_pk_bf16_f32 v177, v8, v9
	global_store_dwordx4 v[154:155], v[174:177], off sc1
	s_nop 1
	s_nop 1
	s_mov_b64 s[12:13], -1
	s_cbranch_vccnz .LBB0_208
	s_andn2_b64 vcc, exec, s[0:1]
	s_cbranch_vccnz .LBB0_207
	s_barrier
	s_branch .LBB0_207
